# v42 + counted lgkmcnt waits in the neighbourhood-attention PV section (two per 4-MFMA block instead of a full drain)
# baseline (speedup 1.0000x reference)
; __device__ __forceinline__ int crow(int r, int hi) { return (r & 3) + 8 * (r >> 2) + 4 * hi; }
;   p0 = f32x16{}; p1 = f32x16{};
; #pragma unroll
;   for (int d0 = DLO; d0 < DHI; ++d0) { int cb = (d0 * 16 + hi * 8) * 2;
;     bf16x8 b0 = *reinterpret_cast<const bf16x8*>((const char*)Ks + KSWZ(r32, cb));
;     bf16x8 b1 = *reinterpret_cast<const bf16x8*>((const char*)Ks + KSWZ(32 + r32, cb));
;     p0 = __builtin_amdgcn_mfma_f32_32x32x16_bf16(b0, qr[d0], p0, 0, 0, 0);
;     p1 = __builtin_amdgcn_mfma_f32_32x32x16_bf16(b1, qr[d0], p1, 0, 0, 0); }
; }
; __device__ __forceinline__ void na_item(const int g_wave, int b, int r, int hp, const bf16* __restrict__ proj, const float* __restrict__ rpb, bf16* __restrict__ cat, char* lds) {
;     ...
;     const float* bp = btab + (hl * 15 + (kr - r + 7)) * 31;
;     float tmax = NEG;
; #pragma unroll
;     for (int q = 0; q < 16; ++q) {
;       const int j0 = crow(q, hi), j1 = 32 + j0;
;       { const bool ok = (j0 >= cs) && (j0 < cs + 16); int dc = j0 - c + 15; dc = dc < 0 ? 0 : (dc > 30 ? 30 : dc);
;         const float bv = bp[dc]; p0[q] = ok ? fmaf(p0[q], C, bv) : NEG; tmax = fmaxf(tmax, p0[q]); }
;       { const bool ok = (j1 >= cs) && (j1 < cs + 16); int dc = j1 - c + 15; dc = dc < 0 ? 0 : (dc > 30 ? 30 : dc);
;         const float bv = bp[dc]; p1[q] = ok ? fmaf(p1[q], C, bv) : NEG; tmax = fmaxf(tmax, p1[q]); }
;     }
.Lna_active:
	s_barrier
	ds_read_b128 v[230:233], v218
	v_add_u32_e32 v0, v139, v137
	ds_read_b128 v[234:237], v0 offset:8192
	ds_read_b128 v[238:241], v219
	v_add_u32_e32 v0, v139, v141
	ds_read_b128 v[242:245], v0 offset:8192
	ds_read_b128 v[246:249], v220
	v_add_u32_e32 v0, v139, v143
	ds_read_b128 v[186:189], v0 offset:8192
	s_waitcnt lgkmcnt(4)
	v_mfma_f32_32x32x16_bf16 v[82:97], v[230:233], v[122:125], 0
	ds_read_b128 v[230:233], v221
	v_mfma_f32_32x32x16_bf16 v[66:81], v[234:237], v[122:125], 0
	v_add_u32_e32 v0, v139, v145
	ds_read_b128 v[234:237], v0 offset:8192
	s_waitcnt lgkmcnt(4)
	v_mfma_f32_32x32x16_bf16 v[82:97], v[238:241], v[98:101], v[82:97]
	ds_read_b128 v[238:241], v222
	v_mfma_f32_32x32x16_bf16 v[66:81], v[242:245], v[98:101], v[66:81]
	v_add_u32_e32 v0, v139, v149
	ds_read_b128 v[242:245], v0 offset:8192
	s_waitcnt lgkmcnt(4)
	v_mfma_f32_32x32x16_bf16 v[82:97], v[246:249], v[102:105], v[82:97]
	ds_read_b128 v[246:249], v223
	v_mfma_f32_32x32x16_bf16 v[66:81], v[186:189], v[102:105], v[66:81]
	v_add_u32_e32 v0, v139, v151
	ds_read_b128 v[186:189], v0 offset:8192
	s_waitcnt lgkmcnt(4)
	v_mfma_f32_32x32x16_bf16 v[82:97], v[230:233], v[106:109], v[82:97]
	ds_read_b128 v[230:233], v224
	v_mfma_f32_32x32x16_bf16 v[66:81], v[234:237], v[106:109], v[66:81]
	v_add_u32_e32 v0, v139, v153
	ds_read_b128 v[234:237], v0 offset:8192
	s_waitcnt lgkmcnt(4)
	v_mfma_f32_32x32x16_bf16 v[82:97], v[238:241], v[110:113], v[82:97]
	ds_read_b128 v[238:241], v225
	v_mfma_f32_32x32x16_bf16 v[66:81], v[242:245], v[110:113], v[66:81]
	v_add_u32_e32 v0, v139, v155
	ds_read_b128 v[242:245], v0 offset:8192
	s_waitcnt lgkmcnt(4)
	v_mfma_f32_32x32x16_bf16 v[82:97], v[246:249], v[114:117], v[82:97]
	v_mfma_f32_32x32x16_bf16 v[66:81], v[186:189], v[114:117], v[66:81]
	s_waitcnt lgkmcnt(2)
	v_mfma_f32_32x32x16_bf16 v[82:97], v[230:233], v[118:121], v[82:97]
	v_mfma_f32_32x32x16_bf16 v[66:81], v[234:237], v[118:121], v[66:81]
	s_waitcnt lgkmcnt(0)
	v_mfma_f32_32x32x16_bf16 v[82:97], v[238:241], v[126:129], v[82:97]
	v_mfma_f32_32x32x16_bf16 v[66:81], v[242:245], v[126:129], v[66:81]
	v_mov_b32_e32 v244, 0xf149f2ca
	v_add_u32_e32 v230, s43, v157
	ds_read_b32 v230, v230
	v_add_u32_e32 v231, s43, v159
	ds_read_b32 v231, v231
	v_add_u32_e32 v232, s43, v161
	ds_read_b32 v232, v232
	v_add_u32_e32 v233, s43, v164
	ds_read_b32 v233, v233
	v_add_u32_e32 v234, s43, v165
	ds_read_b32 v234, v234
	v_add_u32_e32 v235, s43, v166
	ds_read_b32 v235, v235
	v_add_u32_e32 v236, s43, v167
	ds_read_b32 v236, v236
	v_add_u32_e32 v237, s43, v168
	ds_read_b32 v237, v237
	v_add_u32_e32 v238, s43, v169
	ds_read_b32 v238, v238
	v_add_u32_e32 v239, s43, v170
	ds_read_b32 v239, v239
	v_add_u32_e32 v240, s43, v171
	ds_read_b32 v240, v240
	v_add_u32_e32 v241, s43, v172
	ds_read_b32 v241, v241
	v_add_u32_e32 v242, s43, v173
	ds_read_b32 v242, v242
	v_add_u32_e32 v243, s43, v174
	ds_read_b32 v243, v243
	s_waitcnt lgkmcnt(12)
	v_fmac_f32_e32 v230, 0x3e0293ee, v82
	v_cndmask_b32_e64 v229, v244, v230, s[26:27]
	v_add_u32_e32 v230, s43, v175
	ds_read_b32 v230, v230
	v_fmac_f32_e32 v231, 0x3e0293ee, v66
	v_cndmask_b32_e64 v228, v244, v231, s[28:29]
	v_add_u32_e32 v231, s43, v176
	ds_read_b32 v231, v231
	s_waitcnt lgkmcnt(12)
	v_fmac_f32_e32 v232, 0x3e0293ee, v83
	v_cndmask_b32_e64 v82, v244, v232, s[30:31]
	v_add_u32_e32 v232, s43, v177
	ds_read_b32 v232, v232
	v_fmac_f32_e32 v233, 0x3e0293ee, v67
	v_cndmask_b32_e64 v66, v244, v233, s[82:83]
	v_add_u32_e32 v233, s43, v190
	ds_read_b32 v233, v233
	s_waitcnt lgkmcnt(12)
	v_fmac_f32_e32 v234, 0x3e0293ee, v84
	v_cndmask_b32_e64 v83, v244, v234, s[84:85]
	v_add_u32_e32 v234, s43, v191
	ds_read_b32 v234, v234
	v_fmac_f32_e32 v235, 0x3e0293ee, v68
	v_cndmask_b32_e64 v67, v244, v235, s[86:87]
	v_add_u32_e32 v235, s43, v192
	ds_read_b32 v235, v235
	s_waitcnt lgkmcnt(12)
	v_fmac_f32_e32 v236, 0x3e0293ee, v85
	v_cndmask_b32_e64 v84, v244, v236, s[88:89]
	v_add_u32_e32 v236, s43, v193
	ds_read_b32 v236, v236
	v_fmac_f32_e32 v237, 0x3e0293ee, v69
	v_cndmask_b32_e64 v68, v244, v237, s[90:91]
	v_add_u32_e32 v237, s43, v194
	ds_read_b32 v237, v237
	s_waitcnt lgkmcnt(12)
	v_fmac_f32_e32 v238, 0x3e0293ee, v86
	v_cndmask_b32_e64 v85, v244, v238, s[92:93]
	v_add_u32_e32 v238, s43, v195
	ds_read_b32 v238, v238
	v_fmac_f32_e32 v239, 0x3e0293ee, v70
	v_cndmask_b32_e64 v69, v244, v239, s[94:95]
	v_add_u32_e32 v239, s43, v196
	ds_read_b32 v239, v239
	s_waitcnt lgkmcnt(12)
	v_fmac_f32_e32 v240, 0x3e0293ee, v87
	v_cndmask_b32_e64 v86, v244, v240, s[96:97]
	v_add_u32_e32 v240, s43, v197
	ds_read_b32 v240, v240
	v_fmac_f32_e32 v241, 0x3e0293ee, v71
	v_cndmask_b32_e64 v70, v244, v241, s[60:61]
	v_add_u32_e32 v241, s43, v207
	ds_read_b32 v241, v241
	s_waitcnt lgkmcnt(12)
	v_fmac_f32_e32 v242, 0x3e0293ee, v88
	v_cndmask_b32_e64 v87, v244, v242, s[38:39]
	v_add_u32_e32 v242, s43, v208
	ds_read_b32 v242, v242
	v_fmac_f32_e32 v243, 0x3e0293ee, v72
	v_cndmask_b32_e64 v71, v244, v243, s[74:75]
	v_add_u32_e32 v243, s43, v209
	ds_read_b32 v243, v243
	s_waitcnt lgkmcnt(12)
	v_fmac_f32_e32 v230, 0x3e0293ee, v89
	v_cndmask_b32_e64 v88, v244, v230, s[36:37]
	v_add_u32_e32 v230, s43, v210
	ds_read_b32 v230, v230
	v_fmac_f32_e32 v231, 0x3e0293ee, v73
	v_cndmask_b32_e64 v72, v244, v231, s[78:79]
	v_add_u32_e32 v231, s43, v211
	ds_read_b32 v231, v231
	s_waitcnt lgkmcnt(12)
	v_fmac_f32_e32 v232, 0x3e0293ee, v90
	v_cndmask_b32_e64 v89, v244, v232, s[4:5]
	v_add_u32_e32 v232, s43, v212
	ds_read_b32 v232, v232
	v_fmac_f32_e32 v233, 0x3e0293ee, v74
	v_cndmask_b32_e64 v73, v244, v233, s[14:15]
	v_add_u32_e32 v233, s43, v213
	ds_read_b32 v233, v233
	s_waitcnt lgkmcnt(12)
; __device__ __forceinline__ int crow(int r, int hi) { return (r & 3) + 8 * (r >> 2) + 4 * hi; }
; __device__ __forceinline__ void na_item(const int g_wave, int b, int r, int hp, const bf16* __restrict__ proj, const float* __restrict__ rpb, bf16* __restrict__ cat, char* lds) {
;     ...
;     const float* bp = btab + (hl * 15 + (kr - r + 7)) * 31;
;     float tmax = NEG;
; #pragma unroll
;     for (int q = 0; q < 16; ++q) {
;       const int j0 = crow(q, hi), j1 = 32 + j0;
;       { const bool ok = (j0 >= cs) && (j0 < cs + 16); int dc = j0 - c + 15; dc = dc < 0 ? 0 : (dc > 30 ? 30 : dc);
;         const float bv = bp[dc]; p0[q] = ok ? fmaf(p0[q], C, bv) : NEG; tmax = fmaxf(tmax, p0[q]); }
;       { const bool ok = (j1 >= cs) && (j1 < cs + 16); int dc = j1 - c + 15; dc = dc < 0 ? 0 : (dc > 30 ? 30 : dc);
;         const float bv = bp[dc]; p1[q] = ok ? fmaf(p1[q], C, bv) : NEG; tmax = fmaxf(tmax, p1[q]); }
;     }
;     { auto rr = __builtin_amdgcn_permlane32_swap(__float_as_uint(tmax), __float_as_uint(tmax), false, false);
;       tmax = fmaxf(__uint_as_float(rr[0]), __uint_as_float(rr[1])); }
;     const float mn = fmaxf(m_reg, tmax); const float alpha = __builtin_amdgcn_exp2f(m_reg - mn); m_reg = mn;
;     float ps = 0.f;
; #pragma unroll
;     for (int q = 0; q < 16; ++q) { p0[q] = __builtin_amdgcn_exp2f(p0[q] - mn); p1[q] = __builtin_amdgcn_exp2f(p1[q] - mn); ps += p0[q] + p1[q]; }
;     { auto rr = __builtin_amdgcn_permlane32_swap(__float_as_uint(ps), __float_as_uint(ps), false, false);
;       ps = __uint_as_float(rr[0]) + __uint_as_float(rr[1]); }
;     l_reg = l_reg * alpha + ps;
;     bf16x8 pa0, pa1, pa2, pa3;
;     PK4(p0, 0, pa0); PK4(p0, 8, pa1); PK4(p1, 0, pa2); PK4(p1, 8, pa3);
;     if (hi == 0) al_l[r32] = alpha; asm volatile("s_waitcnt lgkmcnt(0)" ::: "memory");
	v_fmac_f32_e32 v234, 0x3e0293ee, v91
	v_cndmask_b32_e64 v90, v244, v234, s[70:71]
	v_fmac_f32_e32 v235, 0x3e0293ee, v75
	v_cndmask_b32_e64 v74, v244, v235, s[76:77]
	s_waitcnt lgkmcnt(10)
	v_fmac_f32_e32 v236, 0x3e0293ee, v92
	v_cndmask_b32_e64 v91, v244, v236, s[12:13]
	v_fmac_f32_e32 v237, 0x3e0293ee, v76
	v_cndmask_b32_e64 v75, v244, v237, s[48:49]
	s_waitcnt lgkmcnt(8)
	v_fmac_f32_e32 v238, 0x3e0293ee, v93
	v_cndmask_b32_e64 v92, v244, v238, s[46:47]
	v_fmac_f32_e32 v239, 0x3e0293ee, v77
	v_cndmask_b32_e64 v76, v244, v239, s[2:3]
	s_waitcnt lgkmcnt(6)
	v_fmac_f32_e32 v240, 0x3e0293ee, v94
	v_cndmask_b32_e64 v93, v244, v240, s[50:51]
	v_fmac_f32_e32 v241, 0x3e0293ee, v78
	v_cndmask_b32_e64 v77, v244, v241, s[56:57]
	s_waitcnt lgkmcnt(4)
	v_fmac_f32_e32 v242, 0x3e0293ee, v95
	v_cndmask_b32_e64 v94, v244, v242, s[58:59]
	v_fmac_f32_e32 v243, 0x3e0293ee, v79
	v_cndmask_b32_e64 v78, v244, v243, s[44:45]
	s_waitcnt lgkmcnt(2)
	v_fmac_f32_e32 v230, 0x3e0293ee, v96
	v_cndmask_b32_e64 v95, v244, v230, s[80:81]
	v_fmac_f32_e32 v231, 0x3e0293ee, v80
	v_cndmask_b32_e64 v79, v244, v231, s[34:35]
	s_waitcnt lgkmcnt(0)
	v_fmac_f32_e32 v232, 0x3e0293ee, v97
	v_cndmask_b32_e64 v96, v244, v232, s[72:73]
	v_fmac_f32_e32 v233, 0x3e0293ee, v81
	v_cndmask_b32_e64 v80, v244, v233, s[8:9]
	s_mov_b32 s33, 0xf149f2ca
	v_max3_f32 v0, v229, s33, v228
	v_max3_f32 v0, v0, v82, v66
	v_max3_f32 v0, v0, v83, v67
	v_max3_f32 v0, v0, v84, v68
	v_max3_f32 v0, v0, v85, v69
	v_max3_f32 v0, v0, v86, v70
	v_max3_f32 v0, v0, v87, v71
	v_max3_f32 v0, v0, v88, v72
	v_max3_f32 v0, v0, v89, v73
	v_max3_f32 v0, v0, v90, v74
	v_max3_f32 v0, v0, v91, v75
	v_max3_f32 v0, v0, v92, v76
	v_max3_f32 v0, v0, v93, v77
	v_max3_f32 v0, v0, v94, v78
	v_max3_f32 v0, v0, v95, v79
	v_max3_f32 v0, v0, v96, v80
	v_mov_b32_e32 v81, v0
	s_nop 1
	v_permlane32_swap_b32_e32 v0, v81
	v_max3_f32 v0, v227, v0, v81
	v_sub_f32_e32 v81, v229, v0
	v_sub_f32_e32 v97, v228, v0
	v_exp_f32_e32 v81, v81
	v_exp_f32_e32 v97, v97
	v_sub_f32_e32 v82, v82, v0
	v_sub_f32_e32 v66, v66, v0
	v_exp_f32_e32 v186, v82
	v_exp_f32_e32 v187, v66
	v_sub_f32_e32 v83, v83, v0
	v_sub_f32_e32 v67, v67, v0
	v_sub_f32_e32 v66, v227, v0
	v_exp_f32_e32 v189, v83
	v_exp_f32_e32 v227, v67
	v_sub_f32_e32 v67, v84, v0
	v_sub_f32_e32 v68, v68, v0
	v_exp_f32_e32 v67, v67
	v_exp_f32_e32 v228, v68
	v_add_f32_e32 v82, v81, v97
	v_add_f32_e32 v82, 0, v82
	v_add_f32_e32 v188, v186, v187
	v_add_f32_e32 v68, v188, v82
	v_add_f32_e32 v82, v189, v227
	v_sub_f32_e32 v83, v85, v0
	v_sub_f32_e32 v69, v69, v0
	v_add_f32_e32 v68, v82, v68
	v_add_f32_e32 v82, v67, v228
	v_exp_f32_e32 v85, v83
	v_exp_f32_e32 v188, v69
	v_sub_f32_e32 v69, v86, v0
	v_sub_f32_e32 v70, v70, v0
	v_exp_f32_e32 v69, v69
	v_exp_f32_e32 v86, v70
	v_add_f32_e32 v68, v82, v68
	v_sub_f32_e32 v82, v87, v0
	v_sub_f32_e32 v71, v71, v0
	v_exp_f32_e32 v87, v82
	v_exp_f32_e32 v229, v71
	v_sub_f32_e32 v71, v88, v0
	v_sub_f32_e32 v72, v72, v0
	v_exp_f32_e32 v71, v71
	v_exp_f32_e32 v88, v72
	v_sub_f32_e32 v72, v89, v0
	v_sub_f32_e32 v73, v73, v0
	v_add_f32_e32 v70, v85, v188
	v_exp_f32_e32 v72, v72
	v_exp_f32_e32 v89, v73
	v_sub_f32_e32 v73, v90, v0
	v_sub_f32_e32 v74, v74, v0
	v_add_f32_e32 v68, v70, v68
	v_add_f32_e32 v70, v69, v86
	v_exp_f32_e32 v73, v73
	v_exp_f32_e32 v90, v74
	v_sub_f32_e32 v74, v91, v0
	v_sub_f32_e32 v75, v75, v0
	v_add_f32_e32 v68, v70, v68
	v_add_f32_e32 v70, v87, v229
	v_exp_f32_e32 v74, v74
	v_exp_f32_e32 v91, v75
	v_sub_f32_e32 v75, v92, v0
	v_sub_f32_e32 v76, v76, v0
	v_add_f32_e32 v68, v70, v68
	v_add_f32_e32 v70, v71, v88
	v_exp_f32_e32 v75, v75
	v_exp_f32_e32 v92, v76
	v_sub_f32_e32 v76, v93, v0
	v_sub_f32_e32 v77, v77, v0
	v_add_f32_e32 v68, v70, v68
	v_add_f32_e32 v70, v72, v89
	v_exp_f32_e32 v76, v76
	v_exp_f32_e32 v93, v77
	v_sub_f32_e32 v77, v94, v0
	v_sub_f32_e32 v78, v78, v0
	v_add_f32_e32 v68, v70, v68
	v_add_f32_e32 v70, v73, v90
	v_exp_f32_e32 v77, v77
	v_exp_f32_e32 v94, v78
	v_sub_f32_e32 v78, v95, v0
	v_sub_f32_e32 v79, v79, v0
	v_add_f32_e32 v68, v70, v68
	v_add_f32_e32 v70, v74, v91
	v_exp_f32_e32 v78, v78
	v_exp_f32_e32 v95, v79
	v_sub_f32_e32 v79, v96, v0
	v_sub_f32_e32 v80, v80, v0
	v_add_f32_e32 v68, v70, v68
	v_add_f32_e32 v70, v75, v92
	v_exp_f32_e32 v79, v79
	v_exp_f32_e32 v96, v80
	v_add_f32_e32 v68, v70, v68
	v_add_f32_e32 v70, v76, v93
	v_add_f32_e32 v68, v70, v68
	v_add_f32_e32 v70, v77, v94
	v_add_f32_e32 v68, v70, v68
	v_add_f32_e32 v70, v78, v95
	v_add_f32_e32 v68, v70, v68
	v_add_f32_e32 v70, v79, v96
	v_exp_f32_e32 v82, v66
	v_add_f32_e32 v83, v70, v68
	v_mov_b32_e32 v84, v83
	v_cvt_pk_bf16_f32 v66, v81, v186
	v_cvt_pk_bf16_f32 v67, v189, v67
	v_cvt_pk_bf16_f32 v68, v85, v69
	v_cvt_pk_bf16_f32 v69, v87, v71
	v_cvt_pk_bf16_f32 v70, v72, v73
	v_cvt_pk_bf16_f32 v71, v74, v75
	v_cvt_pk_bf16_f32 v72, v76, v77
	v_cvt_pk_bf16_f32 v73, v78, v79
	v_cvt_pk_bf16_f32 v74, v97, v187
	v_cvt_pk_bf16_f32 v75, v227, v228
	v_cvt_pk_bf16_f32 v76, v188, v86
	v_cvt_pk_bf16_f32 v77, v229, v88
	v_cvt_pk_bf16_f32 v78, v89, v90
	v_cvt_pk_bf16_f32 v79, v91, v92
	v_cvt_pk_bf16_f32 v80, v93, v94
	v_cvt_pk_bf16_f32 v81, v95, v96
	s_nop 1
	v_permlane32_swap_b32_e32 v83, v84
	v_permlane32_swap_b32_e32 v66, v68
	v_permlane32_swap_b32_e32 v67, v69
	v_permlane32_swap_b32_e32 v70, v72
	v_permlane32_swap_b32_e32 v71, v73
	v_permlane32_swap_b32_e32 v74, v76
	v_permlane32_swap_b32_e32 v75, v77
	v_permlane32_swap_b32_e32 v78, v80
	v_permlane32_swap_b32_e32 v79, v81
	s_and_saveexec_b64 s[68:69], s[6:7]
	ds_write_b32 v147, v82 offset:128
	s_or_b64 exec, exec, s[68:69]
	v_add_f32_e32 v186, v83, v84
	s_waitcnt lgkmcnt(0)
; #define SBAR() __builtin_amdgcn_sched_barrier(0)
; __device__ __forceinline__ int crow(int r, int hi) { return (r & 3) + 8 * (r >> 2) + 4 * hi; }
; template <int D0> __device__ __forceinline__ void pv_one(f32x16& od, int vb, bf16x8 pa0, bf16x8 pa1, bf16x8 pa2, bf16x8 pa3) {
;   const s16x4 l0 = tr_read<v_rd_off(D0, 0, 0)>(vb), h0 = tr_read<v_rd_off(D0, 0, 1)>(vb), l1 = tr_read<v_rd_off(D0, 1, 0)>(vb), h1 = tr_read<v_rd_off(D0, 1, 1)>(vb);
;   const s16x4 l2 = tr_read<v_rd_off(D0, 2, 0)>(vb), h2 = tr_read<v_rd_off(D0, 2, 1)>(vb), l3 = tr_read<v_rd_off(D0, 3, 0)>(vb), h3 = tr_read<v_rd_off(D0, 3, 1)>(vb);
;   asm volatile("s_waitcnt lgkmcnt(0)" ::: "memory"); SBAR();
;     ...
;   od = __builtin_amdgcn_mfma_f32_32x32x16_bf16(pa0, PK(l0, h0), od, 0, 0, 0);
;   od = __builtin_amdgcn_mfma_f32_32x32x16_bf16(pa1, PK(l1, h1), od, 0, 0, 0);
;   od = __builtin_amdgcn_mfma_f32_32x32x16_bf16(pa2, PK(l2, h2), od, 0, 0, 0);
;   od = __builtin_amdgcn_mfma_f32_32x32x16_bf16(pa3, PK(l3, h3), od, 0, 0, 0);
;     ...
; }
; __device__ __forceinline__ void na_item(const int g_wave, int b, int r, int hp, const bf16* __restrict__ proj, const float* __restrict__ rpb, bf16* __restrict__ cat, char* lds) {
;     ...
;     if (hi == 0) al_l[r32] = alpha; asm volatile("s_waitcnt lgkmcnt(0)" ::: "memory");
; #pragma unroll
;     for (int d = 0; d < 4; ++d)
; #pragma unroll
;       for (int q = 0; q < 16; ++q) o[d][q] *= al_l[crow(q, hi)];
;     pv_d0(o, vb, pa0, pa1, pa2, pa3);
	v_add_u32_e32 v94, s42, v135
	v_fmac_f32_e32 v186, v226, v82
	ds_read_b128 v[82:85], v94 offset:128
	ds_read_b128 v[86:89], v94 offset:160
	ds_read_b128 v[90:93], v94 offset:192
	ds_read_b128 v[94:97], v94 offset:224
	s_waitcnt lgkmcnt(3)
	v_pk_mul_f32 v[50:51], v[50:51], v[82:83]
	v_pk_mul_f32 v[34:35], v[34:35], v[82:83]
	v_pk_mul_f32 v[18:19], v[18:19], v[82:83]
	v_pk_mul_f32 v[2:3], v[2:3], v[82:83]
	ds_read_b64_tr_b16 v[82:83], v133 offset:0
	v_pk_mul_f32 v[52:53], v[52:53], v[84:85]
	v_pk_mul_f32 v[36:37], v[36:37], v[84:85]
	v_pk_mul_f32 v[20:21], v[20:21], v[84:85]
	v_pk_mul_f32 v[4:5], v[4:5], v[84:85]
	ds_read_b64_tr_b16 v[84:85], v133 offset:0x800
	s_waitcnt lgkmcnt(2)
	v_pk_mul_f32 v[54:55], v[54:55], v[86:87]
	v_pk_mul_f32 v[38:39], v[38:39], v[86:87]
	v_pk_mul_f32 v[22:23], v[22:23], v[86:87]
	v_pk_mul_f32 v[6:7], v[6:7], v[86:87]
	ds_read_b64_tr_b16 v[86:87], v133 offset:0x1000
	v_pk_mul_f32 v[56:57], v[56:57], v[88:89]
	v_pk_mul_f32 v[40:41], v[40:41], v[88:89]
	v_pk_mul_f32 v[24:25], v[24:25], v[88:89]
	v_pk_mul_f32 v[8:9], v[8:9], v[88:89]
	ds_read_b64_tr_b16 v[88:89], v133 offset:0x1800
	s_waitcnt lgkmcnt(1)
	v_pk_mul_f32 v[58:59], v[58:59], v[90:91]
	v_pk_mul_f32 v[42:43], v[42:43], v[90:91]
	v_pk_mul_f32 v[26:27], v[26:27], v[90:91]
	v_pk_mul_f32 v[10:11], v[10:11], v[90:91]
	ds_read_b64_tr_b16 v[90:91], v133 offset:0x2000
	v_pk_mul_f32 v[60:61], v[60:61], v[92:93]
	v_pk_mul_f32 v[44:45], v[44:45], v[92:93]
	v_pk_mul_f32 v[28:29], v[28:29], v[92:93]
	v_pk_mul_f32 v[12:13], v[12:13], v[92:93]
	ds_read_b64_tr_b16 v[92:93], v133 offset:0x2800
	s_waitcnt lgkmcnt(0)
	v_pk_mul_f32 v[62:63], v[62:63], v[94:95]
	v_pk_mul_f32 v[46:47], v[46:47], v[94:95]
	v_pk_mul_f32 v[30:31], v[30:31], v[94:95]
	v_pk_mul_f32 v[14:15], v[14:15], v[94:95]
	ds_read_b64_tr_b16 v[94:95], v133 offset:0x3000
	v_pk_mul_f32 v[64:65], v[64:65], v[96:97]
	v_pk_mul_f32 v[48:49], v[48:49], v[96:97]
	v_pk_mul_f32 v[32:33], v[32:33], v[96:97]
	v_pk_mul_f32 v[16:17], v[16:17], v[96:97]
	ds_read_b64_tr_b16 v[96:97], v133 offset:0x3800
	s_waitcnt lgkmcnt(0)
	v_mfma_f32_32x32x16_bf16 v[50:65], v[66:69], v[82:85], v[50:65]
	ds_read_b64_tr_b16 v[82:83], v133 offset:0x200
	ds_read_b64_tr_b16 v[84:85], v133 offset:0xa00
	v_mfma_f32_32x32x16_bf16 v[50:65], v[70:73], v[86:89], v[50:65]
	ds_read_b64_tr_b16 v[86:87], v133 offset:0x1200
	ds_read_b64_tr_b16 v[88:89], v133 offset:0x1a00
	v_mfma_f32_32x32x16_bf16 v[50:65], v[74:77], v[90:93], v[50:65]
	ds_read_b64_tr_b16 v[90:91], v133 offset:0x2200
	ds_read_b64_tr_b16 v[92:93], v133 offset:0x2a00
	v_mfma_f32_32x32x16_bf16 v[50:65], v[78:81], v[94:97], v[50:65]
	ds_read_b64_tr_b16 v[94:95], v133 offset:0x3200
	ds_read_b64_tr_b16 v[96:97], v133 offset:0x3a00
	s_waitcnt lgkmcnt(4)
	v_mfma_f32_32x32x16_bf16 v[34:49], v[66:69], v[82:85], v[34:49]
	ds_read_b64_tr_b16 v[82:83], v133 offset:0x400
	ds_read_b64_tr_b16 v[84:85], v133 offset:0xc00
	v_mfma_f32_32x32x16_bf16 v[34:49], v[70:73], v[86:89], v[34:49]
	ds_read_b64_tr_b16 v[86:87], v133 offset:0x1400
	ds_read_b64_tr_b16 v[88:89], v133 offset:0x1c00
	s_waitcnt lgkmcnt(4)
	v_mfma_f32_32x32x16_bf16 v[34:49], v[74:77], v[90:93], v[34:49]
	ds_read_b64_tr_b16 v[90:91], v133 offset:0x2400
	ds_read_b64_tr_b16 v[92:93], v133 offset:0x2c00
	v_mfma_f32_32x32x16_bf16 v[34:49], v[78:81], v[94:97], v[34:49]
	ds_read_b64_tr_b16 v[94:95], v133 offset:0x3400
	ds_read_b64_tr_b16 v[96:97], v133 offset:0x3c00
	s_waitcnt lgkmcnt(4)
	v_mfma_f32_32x32x16_bf16 v[18:33], v[66:69], v[82:85], v[18:33]
	ds_read_b64_tr_b16 v[82:83], v133 offset:0x600
	ds_read_b64_tr_b16 v[84:85], v133 offset:0xe00
	v_mfma_f32_32x32x16_bf16 v[18:33], v[70:73], v[86:89], v[18:33]
	ds_read_b64_tr_b16 v[86:87], v133 offset:0x1600
	ds_read_b64_tr_b16 v[88:89], v133 offset:0x1e00
	s_waitcnt lgkmcnt(4)
	v_mfma_f32_32x32x16_bf16 v[18:33], v[74:77], v[90:93], v[18:33]
	ds_read_b64_tr_b16 v[90:91], v133 offset:0x2600
	ds_read_b64_tr_b16 v[92:93], v133 offset:0x2e00
	v_mfma_f32_32x32x16_bf16 v[18:33], v[78:81], v[94:97], v[18:33]
	ds_read_b64_tr_b16 v[94:95], v133 offset:0x3600
	ds_read_b64_tr_b16 v[96:97], v133 offset:0x3e00
	s_waitcnt lgkmcnt(4)
	v_mfma_f32_32x32x16_bf16 v[2:17], v[66:69], v[82:85], v[2:17]
	v_mov_b32_e32 v226, v186
	v_mfma_f32_32x32x16_bf16 v[2:17], v[70:73], v[86:89], v[2:17]
	s_waitcnt lgkmcnt(0)
	v_mfma_f32_32x32x16_bf16 v[2:17], v[74:77], v[90:93], v[2:17]
	v_mfma_f32_32x32x16_bf16 v[2:17], v[78:81], v[94:97], v[2:17]
	s_addk_i32 s43, 0x7c
	s_cmpk_eq_i32 s43, 0x3e0
	v_lshl_add_u64 v[162:163], v[162:163], 0, s[54:55]
	s_cbranch_scc0 .LBB0_1145
	s_branch .LBB0_1146
